# second copies of the retention and differential item epilogues get the same batched-load / counted-vmcnt treatment
# speedup vs baseline: 1.0095x; 1.0041x over previous
.LBB0_844:
	s_or_b64 exec, exec, s[26:27]
	s_and_b32 s0, s58, 0x60
	v_add_u32_e32 v66, s7, v188
	s_lshl_b32 s0, s0, 2
	v_ashrrev_i32_e32 v67, 31, v66
	s_add_i32 s0, s0, 0
	v_lshlrev_b64 v[68:69], 12, v[66:67]
	s_ashr_i32 s7, s6, 31
	v_mov_b64_e32 v[70:71], s[20:21]
	s_movk_i32 s4, 0x3000
	v_lshl_add_u32 v64, v188, 2, s0
	v_lshl_add_u64 v[68:69], s[20:21], 0, v[68:69]
	s_lshl_b64 s[0:1], s[6:7], 1
	v_mad_i64_i32 v[66:67], s[4:5], v66, s4, v[70:71]
	s_waitcnt lgkmcnt(0)
	s_barrier
	v_lshl_add_u64 v[68:69], v[68:69], 0, s[0:1]
	v_lshl_add_u64 v[66:67], v[66:67], 0, s[0:1]
	s_load_dwordx2 s[0:1], s[66:67], 0xc0
	s_lshl_b64 s[4:5], s[6:7], 2
	v_lshlrev_b32_e32 v74, 1, v189
	v_mov_b32_e32 v75, v112
	v_lshl_add_u64 v[70:71], v[66:67], 0, v[74:75]
	s_waitcnt lgkmcnt(0)
	s_add_u32 s6, s0, s4
	s_addc_u32 s7, s1, s5
	s_mov_b64 s[0:1], 0x4802000
	v_lshl_add_u64 v[66:67], v[70:71], 0, s[0:1]
	s_mov_b32 s0, 0x4802000
	v_add_co_u32_e32 v70, vcc, s0, v70
	v_lshlrev_b32_e32 v65, 2, v189
	s_nop 0
	v_addc_co_u32_e32 v71, vcc, 0, v71, vcc
	global_load_dwordx2 v[76:77], v[70:71], off
	ds_read_b32 v64, v64 offset:1024
	global_load_dwordx4 v[70:73], v65, s[6:7]
	global_load_dwordx2 v[142:143], v[66:67], off offset:16
	global_load_dwordx4 v[214:217], v65, s[6:7] offset:32
	global_load_dwordx2 v[144:145], v[66:67], off offset:32
	global_load_dwordx4 v[218:221], v65, s[6:7] offset:64
	global_load_dwordx2 v[146:147], v[66:67], off offset:48
	global_load_dwordx4 v[222:225], v65, s[6:7] offset:96
	global_load_dwordx2 v[148:149], v[66:67], off offset:64
	global_load_dwordx4 v[226:229], v65, s[6:7] offset:128
	global_load_dwordx2 v[150:151], v[66:67], off offset:80
	global_load_dwordx4 v[230:233], v65, s[6:7] offset:160
	global_load_dwordx2 v[152:153], v[66:67], off offset:96
	global_load_dwordx4 v[234:237], v65, s[6:7] offset:192
	global_load_dwordx2 v[154:155], v[66:67], off offset:112
	global_load_dwordx4 v[238:241], v65, s[6:7] offset:224
	global_load_dwordx2 v[156:157], v[66:67], off offset:128
	global_load_dwordx4 v[242:245], v65, s[6:7] offset:256
	global_load_dwordx2 v[158:159], v[66:67], off offset:144
	global_load_dwordx4 v[246:249], v65, s[6:7] offset:288
	global_load_dwordx2 v[160:161], v[66:67], off offset:160
	global_load_dwordx4 v[182:185], v65, s[6:7] offset:320
	global_load_dwordx2 v[170:171], v[66:67], off offset:176
	global_load_dwordx4 v[84:87], v65, s[6:7] offset:352
	global_load_dwordx2 v[172:173], v[66:67], off offset:192
	global_load_dwordx4 v[92:95], v65, s[6:7] offset:384
	global_load_dwordx2 v[174:175], v[66:67], off offset:208
	global_load_dwordx4 v[102:105], v65, s[6:7] offset:416
	global_load_dwordx2 v[176:177], v[66:67], off offset:224
	global_load_dwordx4 v[122:125], v65, s[6:7] offset:448
	global_load_dwordx2 v[178:179], v[66:67], off offset:240
	global_load_dwordx4 v[130:133], v65, s[6:7] offset:480
	s_mov_b64 s[0:1], 0x12c00000
	s_waitcnt lgkmcnt(0)
	v_pk_mul_f32 v[48:49], v[48:49], v[64:65] op_sel_hi:[1,0]
	v_pk_mul_f32 v[50:51], v[50:51], v[64:65] op_sel_hi:[1,0]
	v_pk_mul_f32 v[52:53], v[52:53], v[64:65] op_sel_hi:[1,0]
	v_pk_mul_f32 v[54:55], v[54:55], v[64:65] op_sel_hi:[1,0]
	v_pk_mul_f32 v[56:57], v[56:57], v[64:65] op_sel_hi:[1,0]
	v_pk_mul_f32 v[32:33], v[32:33], v[64:65] op_sel_hi:[1,0]
	v_pk_mul_f32 v[34:35], v[34:35], v[64:65] op_sel_hi:[1,0]
	v_pk_mul_f32 v[36:37], v[36:37], v[64:65] op_sel_hi:[1,0]
	v_pk_mul_f32 v[38:39], v[38:39], v[64:65] op_sel_hi:[1,0]
	v_pk_mul_f32 v[40:41], v[40:41], v[64:65] op_sel_hi:[1,0]
	v_pk_mul_f32 v[16:17], v[16:17], v[64:65] op_sel_hi:[1,0]
	v_pk_mul_f32 v[18:19], v[18:19], v[64:65] op_sel_hi:[1,0]
	v_pk_mul_f32 v[20:21], v[20:21], v[64:65] op_sel_hi:[1,0]
	v_pk_mul_f32 v[22:23], v[22:23], v[64:65] op_sel_hi:[1,0]
	v_pk_mul_f32 v[24:25], v[24:25], v[64:65] op_sel_hi:[1,0]
	v_pk_mul_f32 v[0:1], v[0:1], v[64:65] op_sel_hi:[1,0]
	v_pk_mul_f32 v[2:3], v[2:3], v[64:65] op_sel_hi:[1,0]
	v_pk_mul_f32 v[4:5], v[4:5], v[64:65] op_sel_hi:[1,0]
	v_pk_mul_f32 v[6:7], v[6:7], v[64:65] op_sel_hi:[1,0]
	v_pk_mul_f32 v[8:9], v[8:9], v[64:65] op_sel_hi:[1,0]
	s_waitcnt vmcnt(31)
	v_lshlrev_b32_e32 v78, 16, v76
	v_and_b32_e32 v79, 0xffff0000, v76
	v_mul_f32_e32 v76, 0xbfb8aa3b, v78
	v_exp_f32_e32 v76, v76
	s_waitcnt vmcnt(30)
	v_pk_mul_f32 v[48:49], v[48:49], v[70:71]
	v_lshlrev_b32_e32 v70, 16, v77
	v_and_b32_e32 v71, 0xffff0000, v77
	v_add_f32_e32 v76, 1.0, v76
	v_rcp_f32_e32 v80, v76
	v_mul_f32_e32 v76, 0xbfb8aa3b, v79
	v_exp_f32_e32 v76, v76
	v_mul_f32_e32 v77, 0xbfb8aa3b, v71
	v_exp_f32_e32 v77, v77
	v_pk_mul_f32 v[50:51], v[50:51], v[72:73]
	v_add_f32_e32 v76, 1.0, v76
	v_rcp_f32_e32 v81, v76
	v_mul_f32_e32 v76, 0xbfb8aa3b, v70
	v_exp_f32_e32 v76, v76
	v_add_f32_e32 v77, 1.0, v77
	v_rcp_f32_e32 v77, v77
	v_pk_mul_f32 v[78:79], v[80:81], v[78:79]
	v_add_f32_e32 v76, 1.0, v76
	v_rcp_f32_e32 v76, v76
	v_pk_mul_f32 v[48:49], v[48:49], v[78:79]
	v_pk_mul_f32 v[70:71], v[76:77], v[70:71]
	s_nop 0
	v_pk_mul_f32 v[50:51], v[50:51], v[70:71]
	v_cvt_pk_bf16_f32 v70, v48, v49
	v_cvt_pk_bf16_f32 v71, v50, v51
	v_lshl_add_u64 v[50:51], v[68:69], 0, v[74:75]
	v_lshl_add_u64 v[48:49], v[50:51], 0, s[0:1]
	s_mov_b32 s0, 0x12c00000
	v_add_co_u32_e32 v50, vcc, s0, v50
	s_nop 1
	v_addc_co_u32_e32 v51, vcc, 0, v51, vcc
	global_store_dwordx2 v[50:51], v[70:71], off
	s_nop 0
	s_waitcnt vmcnt(30)
	v_lshlrev_b32_e32 v72, 16, v142
	v_and_b32_e32 v73, 0xffff0000, v142
	v_mul_f32_e32 v50, 0xbfb8aa3b, v72
	v_exp_f32_e32 v50, v50
	s_waitcnt vmcnt(29)
	v_pk_mul_f32 v[52:53], v[52:53], v[214:215]
	v_pk_mul_f32 v[54:55], v[54:55], v[216:217]
	v_add_f32_e32 v50, 1.0, v50
	v_rcp_f32_e32 v74, v50
	v_mul_f32_e32 v50, 0xbfb8aa3b, v73
	v_exp_f32_e32 v50, v50
	s_nop 0
	v_add_f32_e32 v50, 1.0, v50
	v_rcp_f32_e32 v75, v50
	v_lshlrev_b32_e32 v50, 16, v143
	v_and_b32_e32 v51, 0xffff0000, v143
	v_mul_f32_e32 v68, 0xbfb8aa3b, v50
	v_mul_f32_e32 v69, 0xbfb8aa3b, v51
	v_exp_f32_e32 v68, v68
	v_exp_f32_e32 v69, v69
	v_pk_mul_f32 v[72:73], v[74:75], v[72:73]
	v_add_f32_e32 v68, 1.0, v68
	v_add_f32_e32 v69, 1.0, v69
	v_rcp_f32_e32 v68, v68
	v_rcp_f32_e32 v69, v69
	v_pk_mul_f32 v[52:53], v[52:53], v[72:73]
	v_pk_mul_f32 v[50:51], v[68:69], v[50:51]
	s_nop 0
	v_pk_mul_f32 v[50:51], v[54:55], v[50:51]
	v_cvt_pk_bf16_f32 v52, v52, v53
	v_cvt_pk_bf16_f32 v53, v50, v51
	global_store_dwordx2 v[48:49], v[52:53], off offset:16
	s_nop 0
	s_waitcnt vmcnt(29)
	v_lshlrev_b32_e32 v68, 16, v144
	v_and_b32_e32 v69, 0xffff0000, v144
	v_mul_f32_e32 v54, 0xbfb8aa3b, v68
	v_exp_f32_e32 v54, v54
	s_waitcnt vmcnt(28)
	v_pk_mul_f32 v[50:51], v[56:57], v[218:219]
	v_add_f32_e32 v54, 1.0, v54
	v_rcp_f32_e32 v70, v54
	v_mul_f32_e32 v54, 0xbfb8aa3b, v69
	v_exp_f32_e32 v54, v54
	s_nop 0
	v_add_f32_e32 v54, 1.0, v54
	v_rcp_f32_e32 v71, v54
	v_lshlrev_b32_e32 v54, 16, v145
	v_and_b32_e32 v55, 0xffff0000, v145
	v_mul_f32_e32 v56, 0xbfb8aa3b, v54
	v_mul_f32_e32 v57, 0xbfb8aa3b, v55
	v_exp_f32_e32 v56, v56
	v_exp_f32_e32 v57, v57
	v_pk_mul_f32 v[68:69], v[70:71], v[68:69]
	v_add_f32_e32 v56, 1.0, v56
	v_add_f32_e32 v57, 1.0, v57
	v_rcp_f32_e32 v56, v56
	v_rcp_f32_e32 v57, v57
	v_pk_mul_f32 v[50:51], v[50:51], v[68:69]
	v_pk_mul_f32 v[54:55], v[56:57], v[54:55]
	v_pk_mul_f32 v[56:57], v[58:59], v[64:65] op_sel_hi:[1,0]
	v_cvt_pk_bf16_f32 v50, v50, v51
	v_pk_mul_f32 v[52:53], v[56:57], v[220:221]
	s_nop 0
	v_pk_mul_f32 v[52:53], v[52:53], v[54:55]
	s_nop 0
	v_cvt_pk_bf16_f32 v51, v52, v53
	global_store_dwordx2 v[48:49], v[50:51], off offset:32
	s_nop 0
	s_waitcnt vmcnt(28)
	v_lshlrev_b32_e32 v56, 16, v146
	v_and_b32_e32 v57, 0xffff0000, v146
	v_mul_f32_e32 v54, 0xbfb8aa3b, v56
	v_exp_f32_e32 v54, v54
	s_nop 0
	v_add_f32_e32 v54, 1.0, v54
	v_rcp_f32_e32 v58, v54
	v_mul_f32_e32 v54, 0xbfb8aa3b, v57
	v_exp_f32_e32 v54, v54
	s_nop 0
	v_add_f32_e32 v54, 1.0, v54
	v_rcp_f32_e32 v59, v54
	v_lshlrev_b32_e32 v54, 16, v147
	v_and_b32_e32 v55, 0xffff0000, v147
	v_pk_mul_f32 v[56:57], v[58:59], v[56:57]
	v_pk_mul_f32 v[58:59], v[60:61], v[64:65] op_sel_hi:[1,0]
	s_waitcnt vmcnt(27)
	v_pk_mul_f32 v[50:51], v[58:59], v[222:223]
	s_nop 0
	v_pk_mul_f32 v[50:51], v[50:51], v[56:57]
	v_mul_f32_e32 v56, 0xbfb8aa3b, v54
	v_mul_f32_e32 v57, 0xbfb8aa3b, v55
	v_exp_f32_e32 v56, v56
	v_exp_f32_e32 v57, v57
	v_cvt_pk_bf16_f32 v50, v50, v51
	v_add_f32_e32 v56, 1.0, v56
	v_add_f32_e32 v57, 1.0, v57
	v_rcp_f32_e32 v56, v56
	v_rcp_f32_e32 v57, v57
	s_nop 0
	v_pk_mul_f32 v[54:55], v[56:57], v[54:55]
	v_pk_mul_f32 v[56:57], v[62:63], v[64:65] op_sel_hi:[1,0]
	s_nop 0
	v_pk_mul_f32 v[52:53], v[56:57], v[224:225]
	s_nop 0
	v_pk_mul_f32 v[52:53], v[52:53], v[54:55]
	s_nop 0
	v_cvt_pk_bf16_f32 v51, v52, v53
	global_store_dwordx2 v[48:49], v[50:51], off offset:48
	s_nop 0
	s_waitcnt vmcnt(27)
	v_lshlrev_b32_e32 v56, 16, v148
	v_and_b32_e32 v57, 0xffff0000, v148
	v_mul_f32_e32 v54, 0xbfb8aa3b, v56
	v_exp_f32_e32 v54, v54
	s_waitcnt vmcnt(26)
	v_pk_mul_f32 v[32:33], v[32:33], v[226:227]
	v_lshlrev_b32_e32 v50, 16, v149
	v_and_b32_e32 v51, 0xffff0000, v149
	v_add_f32_e32 v54, 1.0, v54
	v_rcp_f32_e32 v58, v54
	v_mul_f32_e32 v54, 0xbfb8aa3b, v57
	v_exp_f32_e32 v54, v54
	v_mul_f32_e32 v55, 0xbfb8aa3b, v51
	v_exp_f32_e32 v55, v55
	v_pk_mul_f32 v[34:35], v[34:35], v[228:229]
	v_add_f32_e32 v54, 1.0, v54
	v_rcp_f32_e32 v59, v54
	v_mul_f32_e32 v54, 0xbfb8aa3b, v50
	v_exp_f32_e32 v54, v54
	v_add_f32_e32 v55, 1.0, v55
	v_rcp_f32_e32 v55, v55
	v_pk_mul_f32 v[56:57], v[58:59], v[56:57]
	v_add_f32_e32 v54, 1.0, v54
	v_rcp_f32_e32 v54, v54
	v_pk_mul_f32 v[32:33], v[32:33], v[56:57]
	v_pk_mul_f32 v[50:51], v[54:55], v[50:51]
	s_nop 0
	v_pk_mul_f32 v[34:35], v[34:35], v[50:51]
	v_cvt_pk_bf16_f32 v32, v32, v33
	v_cvt_pk_bf16_f32 v33, v34, v35
	global_store_dwordx2 v[48:49], v[32:33], off offset:64
	s_nop 0
	s_waitcnt vmcnt(26)
	v_lshlrev_b32_e32 v52, 16, v150
	v_and_b32_e32 v53, 0xffff0000, v150
	v_mul_f32_e32 v50, 0xbfb8aa3b, v52
	v_exp_f32_e32 v50, v50
	s_waitcnt vmcnt(25)
	v_pk_mul_f32 v[32:33], v[36:37], v[230:231]
	v_lshlrev_b32_e32 v36, 16, v151
	v_and_b32_e32 v37, 0xffff0000, v151
	v_add_f32_e32 v50, 1.0, v50
	v_rcp_f32_e32 v54, v50
	v_mul_f32_e32 v50, 0xbfb8aa3b, v53
	v_exp_f32_e32 v50, v50
	v_mul_f32_e32 v51, 0xbfb8aa3b, v37
	v_exp_f32_e32 v51, v51
	v_pk_mul_f32 v[34:35], v[38:39], v[232:233]
	v_add_f32_e32 v50, 1.0, v50
	v_rcp_f32_e32 v55, v50
	v_mul_f32_e32 v50, 0xbfb8aa3b, v36
	v_exp_f32_e32 v50, v50
	v_add_f32_e32 v51, 1.0, v51
	v_rcp_f32_e32 v51, v51
	v_pk_mul_f32 v[52:53], v[54:55], v[52:53]
	v_add_f32_e32 v50, 1.0, v50
	v_rcp_f32_e32 v50, v50
	v_pk_mul_f32 v[32:33], v[32:33], v[52:53]
	v_pk_mul_f32 v[36:37], v[50:51], v[36:37]
	s_nop 0
	v_pk_mul_f32 v[34:35], v[34:35], v[36:37]
	v_cvt_pk_bf16_f32 v32, v32, v33
	v_cvt_pk_bf16_f32 v33, v34, v35
	global_store_dwordx2 v[48:49], v[32:33], off offset:80
	s_nop 0
	s_waitcnt vmcnt(25)
	v_lshlrev_b32_e32 v38, 16, v152
	v_and_b32_e32 v39, 0xffff0000, v152
	v_mul_f32_e32 v36, 0xbfb8aa3b, v38
	v_exp_f32_e32 v36, v36
	s_waitcnt vmcnt(24)
	v_pk_mul_f32 v[32:33], v[40:41], v[234:235]
	v_add_f32_e32 v36, 1.0, v36
	v_rcp_f32_e32 v50, v36
	v_mul_f32_e32 v36, 0xbfb8aa3b, v39
	v_exp_f32_e32 v36, v36
	s_nop 0
	v_add_f32_e32 v36, 1.0, v36
	v_rcp_f32_e32 v51, v36
	v_lshlrev_b32_e32 v36, 16, v153
	v_and_b32_e32 v37, 0xffff0000, v153
	v_pk_mul_f32 v[38:39], v[50:51], v[38:39]
	s_nop 0
	v_pk_mul_f32 v[32:33], v[32:33], v[38:39]
	v_mul_f32_e32 v38, 0xbfb8aa3b, v36
	v_mul_f32_e32 v39, 0xbfb8aa3b, v37
	v_exp_f32_e32 v38, v38
	v_exp_f32_e32 v39, v39
	v_cvt_pk_bf16_f32 v32, v32, v33
	v_add_f32_e32 v38, 1.0, v38
	v_add_f32_e32 v39, 1.0, v39
	v_rcp_f32_e32 v38, v38
	v_rcp_f32_e32 v39, v39
	s_nop 0
	v_pk_mul_f32 v[36:37], v[38:39], v[36:37]
	v_pk_mul_f32 v[38:39], v[42:43], v[64:65] op_sel_hi:[1,0]
	s_nop 0
	v_pk_mul_f32 v[34:35], v[38:39], v[236:237]
	s_nop 0
	v_pk_mul_f32 v[34:35], v[34:35], v[36:37]
	s_nop 0
	v_cvt_pk_bf16_f32 v33, v34, v35
	global_store_dwordx2 v[48:49], v[32:33], off offset:96
	s_nop 0
	s_waitcnt vmcnt(24)
	v_lshlrev_b32_e32 v38, 16, v154
	v_and_b32_e32 v39, 0xffff0000, v154
	v_mul_f32_e32 v36, 0xbfb8aa3b, v38
	v_exp_f32_e32 v36, v36
	s_nop 0
	v_add_f32_e32 v36, 1.0, v36
	v_rcp_f32_e32 v40, v36
	v_mul_f32_e32 v36, 0xbfb8aa3b, v39
	v_exp_f32_e32 v36, v36
	s_nop 0
	v_add_f32_e32 v36, 1.0, v36
	v_rcp_f32_e32 v41, v36
	v_lshlrev_b32_e32 v36, 16, v155
	v_and_b32_e32 v37, 0xffff0000, v155
	v_pk_mul_f32 v[38:39], v[40:41], v[38:39]
	v_pk_mul_f32 v[40:41], v[44:45], v[64:65] op_sel_hi:[1,0]
	s_waitcnt vmcnt(23)
	v_pk_mul_f32 v[32:33], v[40:41], v[238:239]
	s_nop 0
	v_pk_mul_f32 v[32:33], v[32:33], v[38:39]
	v_mul_f32_e32 v38, 0xbfb8aa3b, v36
	v_mul_f32_e32 v39, 0xbfb8aa3b, v37
	v_exp_f32_e32 v38, v38
	v_exp_f32_e32 v39, v39
	v_cvt_pk_bf16_f32 v32, v32, v33
	v_add_f32_e32 v38, 1.0, v38
	v_add_f32_e32 v39, 1.0, v39
	v_rcp_f32_e32 v38, v38
	v_rcp_f32_e32 v39, v39
	s_nop 0
	v_pk_mul_f32 v[36:37], v[38:39], v[36:37]
	v_pk_mul_f32 v[38:39], v[46:47], v[64:65] op_sel_hi:[1,0]
	s_nop 0
	v_pk_mul_f32 v[34:35], v[38:39], v[240:241]
	s_nop 0
	v_pk_mul_f32 v[34:35], v[34:35], v[36:37]
	s_nop 0
	v_cvt_pk_bf16_f32 v33, v34, v35
	global_store_dwordx2 v[48:49], v[32:33], off offset:112
	s_nop 0
	s_waitcnt vmcnt(23)
	v_lshlrev_b32_e32 v38, 16, v156
	v_and_b32_e32 v39, 0xffff0000, v156
	v_mul_f32_e32 v36, 0xbfb8aa3b, v38
	v_exp_f32_e32 v36, v36
	s_waitcnt vmcnt(22)
	v_pk_mul_f32 v[16:17], v[16:17], v[242:243]
	v_lshlrev_b32_e32 v32, 16, v157
	v_and_b32_e32 v33, 0xffff0000, v157
	v_add_f32_e32 v36, 1.0, v36
	v_rcp_f32_e32 v40, v36
	v_mul_f32_e32 v36, 0xbfb8aa3b, v39
	v_exp_f32_e32 v36, v36
	v_mul_f32_e32 v37, 0xbfb8aa3b, v33
	v_exp_f32_e32 v37, v37
	v_pk_mul_f32 v[18:19], v[18:19], v[244:245]
	v_add_f32_e32 v36, 1.0, v36
	v_rcp_f32_e32 v41, v36
	v_mul_f32_e32 v36, 0xbfb8aa3b, v32
	v_exp_f32_e32 v36, v36
	v_add_f32_e32 v37, 1.0, v37
	v_rcp_f32_e32 v37, v37
	v_pk_mul_f32 v[38:39], v[40:41], v[38:39]
	v_add_f32_e32 v36, 1.0, v36
	v_rcp_f32_e32 v36, v36
	v_pk_mul_f32 v[16:17], v[16:17], v[38:39]
	v_pk_mul_f32 v[32:33], v[36:37], v[32:33]
	s_nop 0
	v_pk_mul_f32 v[18:19], v[18:19], v[32:33]
	v_cvt_pk_bf16_f32 v16, v16, v17
	v_cvt_pk_bf16_f32 v17, v18, v19
	global_store_dwordx2 v[48:49], v[16:17], off offset:128
	s_nop 0
	s_waitcnt vmcnt(22)
	v_lshlrev_b32_e32 v34, 16, v158
	v_and_b32_e32 v35, 0xffff0000, v158
	v_mul_f32_e32 v32, 0xbfb8aa3b, v34
	v_exp_f32_e32 v32, v32
	s_waitcnt vmcnt(21)
	v_pk_mul_f32 v[16:17], v[20:21], v[246:247]
	v_lshlrev_b32_e32 v20, 16, v159
	v_and_b32_e32 v21, 0xffff0000, v159
	v_add_f32_e32 v32, 1.0, v32
	v_rcp_f32_e32 v36, v32
	v_mul_f32_e32 v32, 0xbfb8aa3b, v35
	v_exp_f32_e32 v32, v32
	v_mul_f32_e32 v33, 0xbfb8aa3b, v21
	v_exp_f32_e32 v33, v33
	v_pk_mul_f32 v[18:19], v[22:23], v[248:249]
	v_add_f32_e32 v32, 1.0, v32
	v_rcp_f32_e32 v37, v32
	v_mul_f32_e32 v32, 0xbfb8aa3b, v20
	v_exp_f32_e32 v32, v32
	v_add_f32_e32 v33, 1.0, v33
	v_rcp_f32_e32 v33, v33
	v_pk_mul_f32 v[34:35], v[36:37], v[34:35]
	v_add_f32_e32 v32, 1.0, v32
	v_rcp_f32_e32 v32, v32
	v_pk_mul_f32 v[16:17], v[16:17], v[34:35]
	v_pk_mul_f32 v[20:21], v[32:33], v[20:21]
	s_nop 0
	v_pk_mul_f32 v[18:19], v[18:19], v[20:21]
	v_cvt_pk_bf16_f32 v16, v16, v17
	v_cvt_pk_bf16_f32 v17, v18, v19
	global_store_dwordx2 v[48:49], v[16:17], off offset:144
	s_nop 0
	s_waitcnt vmcnt(21)
	v_lshlrev_b32_e32 v22, 16, v160
	v_and_b32_e32 v23, 0xffff0000, v160
	v_mul_f32_e32 v20, 0xbfb8aa3b, v22
	v_exp_f32_e32 v20, v20
	s_waitcnt vmcnt(20)
	v_pk_mul_f32 v[16:17], v[24:25], v[182:183]
	v_add_f32_e32 v20, 1.0, v20
	v_rcp_f32_e32 v32, v20
	v_mul_f32_e32 v20, 0xbfb8aa3b, v23
	v_exp_f32_e32 v20, v20
	s_nop 0
	v_add_f32_e32 v20, 1.0, v20
	v_rcp_f32_e32 v33, v20
	v_lshlrev_b32_e32 v20, 16, v161
	v_and_b32_e32 v21, 0xffff0000, v161
	v_pk_mul_f32 v[22:23], v[32:33], v[22:23]
	s_nop 0
	v_pk_mul_f32 v[16:17], v[16:17], v[22:23]
	v_mul_f32_e32 v22, 0xbfb8aa3b, v20
	v_mul_f32_e32 v23, 0xbfb8aa3b, v21
	v_exp_f32_e32 v22, v22
	v_exp_f32_e32 v23, v23
	v_cvt_pk_bf16_f32 v16, v16, v17
	v_add_f32_e32 v22, 1.0, v22
	v_add_f32_e32 v23, 1.0, v23
	v_rcp_f32_e32 v22, v22
	v_rcp_f32_e32 v23, v23
	s_nop 0
	v_pk_mul_f32 v[20:21], v[22:23], v[20:21]
	v_pk_mul_f32 v[22:23], v[26:27], v[64:65] op_sel_hi:[1,0]
	s_nop 0
	v_pk_mul_f32 v[18:19], v[22:23], v[184:185]
	s_nop 0
	v_pk_mul_f32 v[18:19], v[18:19], v[20:21]
	s_nop 0
	v_cvt_pk_bf16_f32 v17, v18, v19
	global_store_dwordx2 v[48:49], v[16:17], off offset:160
	s_nop 0
	s_waitcnt vmcnt(20)
	v_lshlrev_b32_e32 v22, 16, v170
	v_and_b32_e32 v23, 0xffff0000, v170
	v_mul_f32_e32 v20, 0xbfb8aa3b, v22
	v_exp_f32_e32 v20, v20
	s_nop 0
	v_add_f32_e32 v20, 1.0, v20
	v_rcp_f32_e32 v24, v20
	v_mul_f32_e32 v20, 0xbfb8aa3b, v23
	v_exp_f32_e32 v20, v20
	s_nop 0
	v_add_f32_e32 v20, 1.0, v20
	v_rcp_f32_e32 v25, v20
	v_lshlrev_b32_e32 v20, 16, v171
	v_and_b32_e32 v21, 0xffff0000, v171
	v_pk_mul_f32 v[22:23], v[24:25], v[22:23]
	v_pk_mul_f32 v[24:25], v[28:29], v[64:65] op_sel_hi:[1,0]
	s_waitcnt vmcnt(19)
	v_pk_mul_f32 v[16:17], v[24:25], v[84:85]
	s_nop 0
	v_pk_mul_f32 v[16:17], v[16:17], v[22:23]
	v_mul_f32_e32 v22, 0xbfb8aa3b, v20
	v_mul_f32_e32 v23, 0xbfb8aa3b, v21
	v_exp_f32_e32 v22, v22
	v_exp_f32_e32 v23, v23
	v_cvt_pk_bf16_f32 v16, v16, v17
	v_add_f32_e32 v22, 1.0, v22
	v_add_f32_e32 v23, 1.0, v23
	v_rcp_f32_e32 v22, v22
	v_rcp_f32_e32 v23, v23
	s_nop 0
	v_pk_mul_f32 v[20:21], v[22:23], v[20:21]
	v_pk_mul_f32 v[22:23], v[30:31], v[64:65] op_sel_hi:[1,0]
	s_nop 0
	v_pk_mul_f32 v[18:19], v[22:23], v[86:87]
	s_nop 0
	v_pk_mul_f32 v[18:19], v[18:19], v[20:21]
	s_nop 0
	v_cvt_pk_bf16_f32 v17, v18, v19
	global_store_dwordx2 v[48:49], v[16:17], off offset:176
	s_nop 0
	s_waitcnt vmcnt(19)
	v_lshlrev_b32_e32 v22, 16, v172
	v_and_b32_e32 v23, 0xffff0000, v172
	v_mul_f32_e32 v20, 0xbfb8aa3b, v22
	v_exp_f32_e32 v20, v20
	s_waitcnt vmcnt(18)
	v_pk_mul_f32 v[0:1], v[0:1], v[92:93]
	v_lshlrev_b32_e32 v16, 16, v173
	v_and_b32_e32 v17, 0xffff0000, v173
	v_add_f32_e32 v20, 1.0, v20
	v_rcp_f32_e32 v24, v20
	v_mul_f32_e32 v20, 0xbfb8aa3b, v23
	v_exp_f32_e32 v20, v20
	v_mul_f32_e32 v21, 0xbfb8aa3b, v17
	v_exp_f32_e32 v21, v21
	v_pk_mul_f32 v[2:3], v[2:3], v[94:95]
	v_add_f32_e32 v20, 1.0, v20
	v_rcp_f32_e32 v25, v20
	v_mul_f32_e32 v20, 0xbfb8aa3b, v16
	v_exp_f32_e32 v20, v20
	v_add_f32_e32 v21, 1.0, v21
	v_rcp_f32_e32 v21, v21
	v_pk_mul_f32 v[22:23], v[24:25], v[22:23]
	v_add_f32_e32 v20, 1.0, v20
	v_rcp_f32_e32 v20, v20
	v_pk_mul_f32 v[0:1], v[0:1], v[22:23]
	v_pk_mul_f32 v[16:17], v[20:21], v[16:17]
	s_nop 0
	v_pk_mul_f32 v[2:3], v[2:3], v[16:17]
	v_cvt_pk_bf16_f32 v0, v0, v1
	v_cvt_pk_bf16_f32 v1, v2, v3
	global_store_dwordx2 v[48:49], v[0:1], off offset:192
	s_nop 0
	s_waitcnt vmcnt(18)
	v_lshlrev_b32_e32 v18, 16, v174
	v_and_b32_e32 v19, 0xffff0000, v174
	v_mul_f32_e32 v16, 0xbfb8aa3b, v18
	v_exp_f32_e32 v16, v16
	s_waitcnt vmcnt(17)
	v_pk_mul_f32 v[0:1], v[4:5], v[102:103]
	v_lshlrev_b32_e32 v4, 16, v175
	v_and_b32_e32 v5, 0xffff0000, v175
	v_add_f32_e32 v16, 1.0, v16
	v_rcp_f32_e32 v20, v16
	v_mul_f32_e32 v16, 0xbfb8aa3b, v19
	v_exp_f32_e32 v16, v16
	v_mul_f32_e32 v17, 0xbfb8aa3b, v5
	v_exp_f32_e32 v17, v17
	v_pk_mul_f32 v[2:3], v[6:7], v[104:105]
	v_add_f32_e32 v16, 1.0, v16
	v_rcp_f32_e32 v21, v16
	v_mul_f32_e32 v16, 0xbfb8aa3b, v4
	v_exp_f32_e32 v16, v16
	v_add_f32_e32 v17, 1.0, v17
	v_rcp_f32_e32 v17, v17
	v_pk_mul_f32 v[18:19], v[20:21], v[18:19]
	v_add_f32_e32 v16, 1.0, v16
	v_rcp_f32_e32 v16, v16
	v_pk_mul_f32 v[0:1], v[0:1], v[18:19]
	v_pk_mul_f32 v[4:5], v[16:17], v[4:5]
	s_nop 0
	v_pk_mul_f32 v[2:3], v[2:3], v[4:5]
	v_cvt_pk_bf16_f32 v0, v0, v1
	v_cvt_pk_bf16_f32 v1, v2, v3
	global_store_dwordx2 v[48:49], v[0:1], off offset:208
	s_nop 0
	s_waitcnt vmcnt(17)
	v_lshlrev_b32_e32 v6, 16, v176
	v_and_b32_e32 v7, 0xffff0000, v176
	v_mul_f32_e32 v4, 0xbfb8aa3b, v6
	v_exp_f32_e32 v4, v4
	s_waitcnt vmcnt(16)
	v_pk_mul_f32 v[0:1], v[8:9], v[122:123]
	v_add_f32_e32 v4, 1.0, v4
	v_rcp_f32_e32 v16, v4
	v_mul_f32_e32 v4, 0xbfb8aa3b, v7
	v_exp_f32_e32 v4, v4
	s_nop 0
	v_add_f32_e32 v4, 1.0, v4
	v_rcp_f32_e32 v17, v4
	v_lshlrev_b32_e32 v4, 16, v177
	v_and_b32_e32 v5, 0xffff0000, v177
	v_pk_mul_f32 v[6:7], v[16:17], v[6:7]
	s_nop 0
	v_pk_mul_f32 v[0:1], v[0:1], v[6:7]
	v_mul_f32_e32 v6, 0xbfb8aa3b, v4
	v_mul_f32_e32 v7, 0xbfb8aa3b, v5
	v_exp_f32_e32 v6, v6
	v_exp_f32_e32 v7, v7
	v_cvt_pk_bf16_f32 v0, v0, v1
	v_add_f32_e32 v6, 1.0, v6
	v_add_f32_e32 v7, 1.0, v7
	v_rcp_f32_e32 v6, v6
	v_rcp_f32_e32 v7, v7
	s_nop 0
	v_pk_mul_f32 v[4:5], v[6:7], v[4:5]
	v_pk_mul_f32 v[6:7], v[10:11], v[64:65] op_sel_hi:[1,0]
	s_nop 0
	v_pk_mul_f32 v[2:3], v[6:7], v[124:125]
	s_nop 0
	v_pk_mul_f32 v[2:3], v[2:3], v[4:5]
	s_nop 0
	v_cvt_pk_bf16_f32 v1, v2, v3
	global_store_dwordx2 v[48:49], v[0:1], off offset:224
	s_nop 0
	s_waitcnt vmcnt(16)
	v_lshlrev_b32_e32 v6, 16, v178
	v_and_b32_e32 v7, 0xffff0000, v178
	v_mul_f32_e32 v0, 0xbfb8aa3b, v6
	v_exp_f32_e32 v0, v0
	s_nop 0
	v_add_f32_e32 v0, 1.0, v0
	v_rcp_f32_e32 v8, v0
	v_mul_f32_e32 v0, 0xbfb8aa3b, v7
	v_exp_f32_e32 v0, v0
	s_nop 0
	v_add_f32_e32 v0, 1.0, v0
	v_rcp_f32_e32 v9, v0
	v_lshlrev_b32_e32 v0, 16, v179
	v_and_b32_e32 v1, 0xffff0000, v179
	v_pk_mul_f32 v[6:7], v[8:9], v[6:7]
	v_pk_mul_f32 v[8:9], v[12:13], v[64:65] op_sel_hi:[1,0]
	s_waitcnt vmcnt(15)
	v_pk_mul_f32 v[2:3], v[8:9], v[130:131]
	s_nop 0
	v_pk_mul_f32 v[2:3], v[2:3], v[6:7]
	v_mul_f32_e32 v6, 0xbfb8aa3b, v0
	v_mul_f32_e32 v7, 0xbfb8aa3b, v1
	v_exp_f32_e32 v6, v6
	v_exp_f32_e32 v7, v7
	v_cvt_pk_bf16_f32 v2, v2, v3
	v_add_f32_e32 v6, 1.0, v6
	v_add_f32_e32 v7, 1.0, v7
	v_rcp_f32_e32 v6, v6
	v_rcp_f32_e32 v7, v7
	s_nop 0
	v_pk_mul_f32 v[0:1], v[6:7], v[0:1]
	v_pk_mul_f32 v[6:7], v[14:15], v[64:65] op_sel_hi:[1,0]
	s_nop 0
	v_pk_mul_f32 v[4:5], v[6:7], v[132:133]
	s_nop 0
	v_pk_mul_f32 v[0:1], v[4:5], v[0:1]
	s_nop 0
	v_cvt_pk_bf16_f32 v3, v0, v1
	global_store_dwordx2 v[48:49], v[2:3], off offset:240
	s_barrier
	s_cbranch_execnz .LBB0_753
	s_branch .LBB0_800

.LBB0_861:
	s_or_b64 exec, exec, s[20:21]
	v_cmp_gt_i32_e32 vcc, 4, v65
	s_waitcnt lgkmcnt(0)
	s_barrier
	s_and_saveexec_b64 s[20:21], vcc
	s_cbranch_execz .LBB0_851
	v_readlane_b32 s0, v254, 37
	v_lshlrev_b64 v[66:67], 11, v[156:157]
	v_readlane_b32 s1, v254, 38
	v_lshlrev_b32_e32 v65, 8, v151
	v_and_b32_e32 v65, 0xffffc000, v65
	v_lshl_add_u64 v[66:67], s[0:1], 0, v[66:67]
	v_lshl_add_u64 v[78:79], s[6:7], 1, v[66:67]
	v_add3_u32 v66, 0, v64, v65
	ds_read2st64_b32 v[86:87], v66 offset1:1
	ds_read2st64_b32 v[88:89], v66 offset0:2 offset1:3
	ds_read2st64_b32 v[100:101], v66 offset0:4 offset1:5
	ds_read2st64_b32 v[94:95], v66 offset0:6 offset1:7
	ds_read2st64_b32 v[102:103], v66 offset0:8 offset1:9
	ds_read2st64_b32 v[130:131], v66 offset0:10 offset1:11
	ds_read2st64_b32 v[132:133], v66 offset0:12 offset1:13
	ds_read2st64_b32 v[134:135], v66 offset0:14 offset1:15
	ds_read2st64_b32 v[126:127], v66 offset0:16 offset1:17
	ds_read2st64_b32 v[136:137], v66 offset0:18 offset1:19
	ds_read2st64_b32 v[122:123], v66 offset0:20 offset1:21
	ds_read2st64_b32 v[128:129], v66 offset0:22 offset1:23
	ds_read2st64_b32 v[118:119], v66 offset0:24 offset1:25
	ds_read2st64_b32 v[124:125], v66 offset0:26 offset1:27
	ds_read2st64_b32 v[114:115], v66 offset0:28 offset1:29
	ds_read2st64_b32 v[120:121], v66 offset0:30 offset1:31
	ds_read2st64_b32 v[108:109], v66 offset0:32 offset1:33
	ds_read2st64_b32 v[116:117], v66 offset0:34 offset1:35
	ds_read2st64_b32 v[104:105], v66 offset0:36 offset1:37
	ds_read2st64_b32 v[110:111], v66 offset0:38 offset1:39
	ds_read2st64_b32 v[96:97], v66 offset0:40 offset1:41
	ds_read2st64_b32 v[106:107], v66 offset0:42 offset1:43
	ds_read2st64_b32 v[92:93], v66 offset0:44 offset1:45
	ds_read2st64_b32 v[98:99], v66 offset0:46 offset1:47
	ds_read2st64_b32 v[82:83], v66 offset0:48 offset1:49
	ds_read2st64_b32 v[90:91], v66 offset0:50 offset1:51
	ds_read2st64_b32 v[74:75], v66 offset0:52 offset1:53
	ds_read2st64_b32 v[80:81], v66 offset0:54 offset1:55
	ds_read2st64_b32 v[72:73], v66 offset0:56 offset1:57
	ds_read2st64_b32 v[76:77], v66 offset0:58 offset1:59
	ds_read2st64_b32 v[64:65], v66 offset0:60 offset1:61
	v_readlane_b32 s44, v254, 43
	v_readlane_b32 s52, v254, 51
	v_readlane_b32 s53, v254, 52
	v_mov_b32_e32 v155, v112
	s_waitcnt lgkmcnt(0)
	v_pk_mul_f32 v[64:65], v[146:147], v[64:65]
	s_mov_b32 s0, 0x800000
	v_pk_fma_f32 v[64:65], v[12:13], v[68:69], v[64:65] op_sel_hi:[1,0,1] neg_lo:[0,0,1] neg_hi:[0,0,1]
	ds_read2st64_b32 v[12:13], v66 offset0:62 offset1:63
	v_pk_mul_f32 v[70:71], v[64:65], v[64:65]
	v_readlane_b32 s45, v254, 44
	v_readlane_b32 s46, v254, 45
	v_readlane_b32 s47, v254, 46
	s_waitcnt lgkmcnt(0)
	v_pk_mul_f32 v[12:13], v[146:147], v[12:13]
	v_readlane_b32 s48, v254, 47
	v_pk_fma_f32 v[66:67], v[14:15], v[68:69], v[12:13] op_sel_hi:[1,0,1] neg_lo:[0,0,1] neg_hi:[0,0,1]
	v_mov_b32_e32 v12, v192
	v_mov_b32_e32 v13, v112
	v_lshlrev_b32_e32 v12, 2, v12
	v_bitop3_b32 v69, v12, s33, v203 bitop3:0x6c
	v_lshlrev_b32_e32 v12, 11, v113
	v_lshl_add_u64 v[138:139], v[78:79], 0, v[12:13]
	v_pk_mul_f32 v[78:79], v[146:147], v[88:89]
	global_load_dwordx4 v[12:15], v152, s[52:53]
	v_pk_fma_f32 v[78:79], v[50:51], v[68:69], v[78:79] op_sel_hi:[1,0,1] neg_lo:[0,0,1] neg_hi:[0,0,1]
	v_pk_mul_f32 v[50:51], v[146:147], v[86:87]
	v_pk_mul_f32 v[140:141], v[78:79], v[78:79]
	v_pk_fma_f32 v[86:87], v[48:49], v[68:69], v[50:51] op_sel_hi:[1,0,1] neg_lo:[0,0,1] neg_hi:[0,0,1]
	v_pk_mul_f32 v[50:51], v[146:147], v[94:95]
	v_pk_mul_f32 v[142:143], v[86:87], v[86:87]
	v_pk_fma_f32 v[94:95], v[54:55], v[68:69], v[50:51] op_sel_hi:[1,0,1] neg_lo:[0,0,1] neg_hi:[0,0,1]
	v_pk_mul_f32 v[50:51], v[146:147], v[100:101]
	v_lshl_add_u64 v[48:49], v[138:139], 0, v[154:155]
	v_pk_fma_f32 v[100:101], v[52:53], v[68:69], v[50:51] op_sel_hi:[1,0,1] neg_lo:[0,0,1] neg_hi:[0,0,1]
	v_pk_mul_f32 v[50:51], v[146:147], v[130:131]
	v_pk_mul_f32 v[144:145], v[100:101], v[100:101]
	v_pk_fma_f32 v[88:89], v[58:59], v[68:69], v[50:51] op_sel_hi:[1,0,1] neg_lo:[0,0,1] neg_hi:[0,0,1]
	v_pk_mul_f32 v[50:51], v[146:147], v[102:103]
	v_pk_mul_f32 v[138:139], v[94:95], v[94:95]
	v_pk_fma_f32 v[102:103], v[56:57], v[68:69], v[50:51] op_sel_hi:[1,0,1] neg_lo:[0,0,1] neg_hi:[0,0,1]
	v_pk_mul_f32 v[50:51], v[146:147], v[134:135]
	v_pk_mul_f32 v[154:155], v[102:103], v[102:103]
	v_pk_fma_f32 v[58:59], v[62:63], v[68:69], v[50:51] op_sel_hi:[1,0,1] neg_lo:[0,0,1] neg_hi:[0,0,1]
	v_pk_mul_f32 v[50:51], v[146:147], v[132:133]
	v_pk_mul_f32 v[130:131], v[88:89], v[88:89]
	v_pk_fma_f32 v[62:63], v[60:61], v[68:69], v[50:51] op_sel_hi:[1,0,1] neg_lo:[0,0,1] neg_hi:[0,0,1]
	v_pk_mul_f32 v[50:51], v[146:147], v[136:137]
	v_pk_mul_f32 v[132:133], v[62:63], v[62:63]
	v_pk_fma_f32 v[54:55], v[34:35], v[68:69], v[50:51] op_sel_hi:[1,0,1] neg_lo:[0,0,1] neg_hi:[0,0,1]
	v_pk_mul_f32 v[34:35], v[146:147], v[126:127]
	v_pk_mul_f32 v[134:135], v[58:59], v[58:59]
	v_pk_fma_f32 v[60:61], v[32:33], v[68:69], v[34:35] op_sel_hi:[1,0,1] neg_lo:[0,0,1] neg_hi:[0,0,1]
	v_pk_mul_f32 v[32:33], v[146:147], v[128:129]
	v_pk_mul_f32 v[126:127], v[60:61], v[60:61]
	v_pk_fma_f32 v[50:51], v[38:39], v[68:69], v[32:33] op_sel_hi:[1,0,1] neg_lo:[0,0,1] neg_hi:[0,0,1]
	v_pk_mul_f32 v[32:33], v[146:147], v[122:123]
	v_pk_mul_f32 v[136:137], v[54:55], v[54:55]
	v_pk_fma_f32 v[56:57], v[36:37], v[68:69], v[32:33] op_sel_hi:[1,0,1] neg_lo:[0,0,1] neg_hi:[0,0,1]
	v_pk_mul_f32 v[32:33], v[146:147], v[124:125]
	v_pk_mul_f32 v[122:123], v[56:57], v[56:57]
	v_pk_fma_f32 v[42:43], v[42:43], v[68:69], v[32:33] op_sel_hi:[1,0,1] neg_lo:[0,0,1] neg_hi:[0,0,1]
	v_pk_mul_f32 v[32:33], v[146:147], v[118:119]
	v_pk_mul_f32 v[128:129], v[50:51], v[50:51]
	v_pk_fma_f32 v[52:53], v[40:41], v[68:69], v[32:33] op_sel_hi:[1,0,1] neg_lo:[0,0,1] neg_hi:[0,0,1]
	v_pk_mul_f32 v[32:33], v[146:147], v[120:121]
	v_pk_mul_f32 v[118:119], v[52:53], v[52:53]
	v_pk_fma_f32 v[38:39], v[46:47], v[68:69], v[32:33] op_sel_hi:[1,0,1] neg_lo:[0,0,1] neg_hi:[0,0,1]
	v_pk_mul_f32 v[32:33], v[146:147], v[114:115]
	v_pk_mul_f32 v[124:125], v[42:43], v[42:43]
	v_pk_fma_f32 v[44:45], v[44:45], v[68:69], v[32:33] op_sel_hi:[1,0,1] neg_lo:[0,0,1] neg_hi:[0,0,1]
	v_pk_mul_f32 v[32:33], v[146:147], v[116:117]
	v_pk_mul_f32 v[114:115], v[44:45], v[44:45]
	v_pk_fma_f32 v[34:35], v[18:19], v[68:69], v[32:33] op_sel_hi:[1,0,1] neg_lo:[0,0,1] neg_hi:[0,0,1]
	v_pk_mul_f32 v[18:19], v[146:147], v[108:109]
	v_pk_mul_f32 v[46:47], v[38:39], v[38:39]
	v_pk_fma_f32 v[40:41], v[16:17], v[68:69], v[18:19] op_sel_hi:[1,0,1] neg_lo:[0,0,1] neg_hi:[0,0,1]
	v_pk_mul_f32 v[16:17], v[146:147], v[110:111]
	v_pk_mul_f32 v[108:109], v[40:41], v[40:41]
	v_pk_fma_f32 v[32:33], v[22:23], v[68:69], v[16:17] op_sel_hi:[1,0,1] neg_lo:[0,0,1] neg_hi:[0,0,1]
	v_pk_mul_f32 v[16:17], v[146:147], v[104:105]
	v_pk_mul_f32 v[116:117], v[34:35], v[34:35]
	v_pk_fma_f32 v[36:37], v[20:21], v[68:69], v[16:17] op_sel_hi:[1,0,1] neg_lo:[0,0,1] neg_hi:[0,0,1]
	v_pk_mul_f32 v[16:17], v[146:147], v[106:107]
	v_pk_mul_f32 v[104:105], v[36:37], v[36:37]
	v_pk_fma_f32 v[22:23], v[26:27], v[68:69], v[16:17] op_sel_hi:[1,0,1] neg_lo:[0,0,1] neg_hi:[0,0,1]
	v_pk_mul_f32 v[16:17], v[146:147], v[96:97]
	v_pk_mul_f32 v[110:111], v[32:33], v[32:33]
	v_pk_fma_f32 v[26:27], v[24:25], v[68:69], v[16:17] op_sel_hi:[1,0,1] neg_lo:[0,0,1] neg_hi:[0,0,1]
	v_pk_mul_f32 v[16:17], v[146:147], v[98:99]
	v_pk_mul_f32 v[96:97], v[26:27], v[26:27]
	v_pk_fma_f32 v[18:19], v[30:31], v[68:69], v[16:17] op_sel_hi:[1,0,1] neg_lo:[0,0,1] neg_hi:[0,0,1]
	v_pk_mul_f32 v[16:17], v[146:147], v[92:93]
	v_pk_mul_f32 v[106:107], v[22:23], v[22:23]
	v_pk_fma_f32 v[24:25], v[28:29], v[68:69], v[16:17] op_sel_hi:[1,0,1] neg_lo:[0,0,1] neg_hi:[0,0,1]
	v_pk_mul_f32 v[16:17], v[146:147], v[90:91]
	v_pk_mul_f32 v[28:29], v[24:25], v[24:25]
	v_pk_fma_f32 v[16:17], v[2:3], v[68:69], v[16:17] op_sel_hi:[1,0,1] neg_lo:[0,0,1] neg_hi:[0,0,1]
	v_pk_mul_f32 v[2:3], v[146:147], v[82:83]
	v_pk_mul_f32 v[30:31], v[18:19], v[18:19]
	v_pk_fma_f32 v[20:21], v[0:1], v[68:69], v[2:3] op_sel_hi:[1,0,1] neg_lo:[0,0,1] neg_hi:[0,0,1]
	v_pk_mul_f32 v[0:1], v[146:147], v[80:81]
	v_pk_mul_f32 v[82:83], v[20:21], v[20:21]
	v_pk_fma_f32 v[2:3], v[6:7], v[68:69], v[0:1] op_sel_hi:[1,0,1] neg_lo:[0,0,1] neg_hi:[0,0,1]
	v_pk_mul_f32 v[0:1], v[146:147], v[74:75]
	v_pk_mul_f32 v[90:91], v[16:17], v[16:17]
	v_pk_fma_f32 v[6:7], v[4:5], v[68:69], v[0:1] op_sel_hi:[1,0,1] neg_lo:[0,0,1] neg_hi:[0,0,1]
	v_pk_mul_f32 v[0:1], v[146:147], v[76:77]
	v_pk_mul_f32 v[4:5], v[146:147], v[72:73]
	v_pk_fma_f32 v[0:1], v[10:11], v[68:69], v[0:1] op_sel_hi:[1,0,1] neg_lo:[0,0,1] neg_hi:[0,0,1]
	v_pk_fma_f32 v[4:5], v[8:9], v[68:69], v[4:5] op_sel_hi:[1,0,1] neg_lo:[0,0,1] neg_hi:[0,0,1]
	v_add_f32_e32 v68, v142, v143
	v_add_f32_e32 v68, v68, v140
	v_add_f32_e32 v68, v68, v141
	v_add_f32_e32 v68, v68, v144
	v_add_f32_e32 v68, v68, v145
	v_add_f32_e32 v68, v68, v138
	v_add_f32_e32 v68, v68, v139
	v_add_f32_e32 v68, v68, v154
	v_add_f32_e32 v68, v68, v155
	v_add_f32_e32 v68, v68, v130
	v_add_f32_e32 v68, v68, v131
	v_add_f32_e32 v68, v68, v132
	v_add_f32_e32 v68, v68, v133
	v_add_f32_e32 v68, v68, v134
	v_add_f32_e32 v68, v68, v135
	v_add_f32_e32 v68, v68, v126
	v_add_f32_e32 v68, v68, v127
	v_add_f32_e32 v68, v68, v136
	v_add_f32_e32 v68, v68, v137
	v_add_f32_e32 v68, v68, v122
	v_add_f32_e32 v68, v68, v123
	v_add_f32_e32 v68, v68, v128
	v_add_f32_e32 v68, v68, v129
	v_add_f32_e32 v68, v68, v118
	v_add_f32_e32 v68, v68, v119
	v_add_f32_e32 v68, v68, v124
	v_add_f32_e32 v68, v68, v125
	v_add_f32_e32 v68, v68, v114
	v_add_f32_e32 v68, v68, v115
	v_add_f32_e32 v46, v68, v46
	v_add_f32_e32 v46, v46, v47
	v_add_f32_e32 v46, v46, v108
	v_add_f32_e32 v46, v46, v109
	v_add_f32_e32 v46, v46, v116
	v_add_f32_e32 v46, v46, v117
	v_add_f32_e32 v46, v46, v104
	v_add_f32_e32 v46, v46, v105
	v_add_f32_e32 v46, v46, v110
	v_add_f32_e32 v46, v46, v111
	v_add_f32_e32 v46, v46, v96
	v_add_f32_e32 v46, v46, v97
	v_add_f32_e32 v46, v46, v106
	v_add_f32_e32 v46, v46, v107
	v_add_f32_e32 v28, v46, v28
	v_add_f32_e32 v28, v28, v29
	v_add_f32_e32 v28, v28, v30
	v_add_f32_e32 v28, v28, v31
	v_add_f32_e32 v28, v28, v82
	v_add_f32_e32 v28, v28, v83
	v_add_f32_e32 v28, v28, v90
	v_pk_mul_f32 v[74:75], v[6:7], v[6:7]
	v_add_f32_e32 v28, v28, v91
	v_add_f32_e32 v28, v28, v74
	v_pk_mul_f32 v[80:81], v[2:3], v[2:3]
	v_add_f32_e32 v28, v28, v75
	v_add_f32_e32 v28, v28, v80
	v_pk_mul_f32 v[8:9], v[4:5], v[4:5]
	v_add_f32_e32 v28, v28, v81
	v_add_f32_e32 v8, v28, v8
	v_pk_mul_f32 v[10:11], v[0:1], v[0:1]
	v_add_f32_e32 v8, v8, v9
	v_add_f32_e32 v8, v8, v10
	v_add_f32_e32 v8, v8, v11
	v_add_f32_e32 v8, v8, v70
	v_pk_mul_f32 v[84:85], v[66:67], v[66:67]
	v_add_f32_e32 v8, v8, v71
	v_add_f32_e32 v8, v8, v84
	v_add_f32_e32 v8, v8, v85
	ds_bpermute_b32 v9, v69, v8
	v_readlane_b32 s49, v254, 48
	v_readlane_b32 s50, v254, 49
	v_readlane_b32 s51, v254, 50
	v_readlane_b32 s54, v254, 53
	s_waitcnt lgkmcnt(0)
	v_add_f32_e32 v8, v8, v9
	v_fmamk_f32 v8, v8, 0x3c000000, v200
	v_cmp_gt_f32_e32 vcc, s0, v8
	v_mul_f32_e32 v9, 0x4b800000, v8
	v_readlane_b32 s55, v254, 54
	v_cndmask_b32_e32 v8, v8, v9, vcc
	v_rsq_f32_e32 v8, v8
	v_readlane_b32 s56, v254, 55
	v_readlane_b32 s57, v254, 56
	v_readlane_b32 s58, v254, 57
	v_mul_f32_e32 v9, 0x45800000, v8
	v_cndmask_b32_e32 v8, v8, v9, vcc
	v_mul_f32_e32 v8, 0x3f24fd5c, v8
	v_pk_mul_f32 v[10:11], v[86:87], v[8:9] op_sel_hi:[1,0]
	v_pk_mul_f32 v[6:7], v[6:7], v[8:9] op_sel_hi:[1,0]
	global_load_dwordx4 v[214:217], v152, s[52:53] offset:32
	global_load_dwordx4 v[218:221], v152, s[52:53] offset:64
	global_load_dwordx4 v[222:225], v152, s[52:53] offset:96
	global_load_dwordx4 v[226:229], v152, s[52:53] offset:128
	global_load_dwordx4 v[230:233], v152, s[52:53] offset:160
	global_load_dwordx4 v[234:237], v152, s[52:53] offset:192
	global_load_dwordx4 v[238:241], v152, s[52:53] offset:224
	global_load_dwordx4 v[242:245], v152, s[52:53] offset:256
	global_load_dwordx4 v[246:249], v152, s[52:53] offset:288
	global_load_dwordx4 v[142:145], v152, s[52:53] offset:320
	global_load_dwordx4 v[154:157], v152, s[52:53] offset:352
	global_load_dwordx4 v[158:161], v152, s[52:53] offset:384
	global_load_dwordx4 v[170:173], v152, s[52:53] offset:416
	global_load_dwordx4 v[174:177], v152, s[52:53] offset:448
	global_load_dwordx4 v[178:181], v152, s[52:53] offset:480
	s_waitcnt vmcnt(15)
	v_pk_mul_f32 v[10:11], v[12:13], v[10:11]
	v_pk_mul_f32 v[12:13], v[78:79], v[8:9] op_sel_hi:[1,0]
	v_cvt_pk_bf16_f32 v10, v10, v11
	v_pk_mul_f32 v[12:13], v[14:15], v[12:13]
	v_pk_mul_f32 v[14:15], v[100:101], v[8:9] op_sel_hi:[1,0]
	v_cvt_pk_bf16_f32 v11, v12, v13
	global_store_dwordx2 v[48:49], v[10:11], off
	v_pk_mul_f32 v[2:3], v[2:3], v[8:9] op_sel_hi:[1,0]
	v_pk_mul_f32 v[0:1], v[0:1], v[8:9] op_sel_hi:[1,0]
	v_readlane_b32 s59, v254, 58
	s_waitcnt vmcnt(15)
	v_pk_mul_f32 v[10:11], v[214:215], v[14:15]
	v_pk_mul_f32 v[14:15], v[94:95], v[8:9] op_sel_hi:[1,0]
	v_cvt_pk_bf16_f32 v10, v10, v11
	v_pk_mul_f32 v[12:13], v[216:217], v[14:15]
	v_pk_mul_f32 v[14:15], v[102:103], v[8:9] op_sel_hi:[1,0]
	v_cvt_pk_bf16_f32 v11, v12, v13
	global_store_dwordx2 v[48:49], v[10:11], off offset:16
	s_waitcnt vmcnt(15)
	v_pk_mul_f32 v[10:11], v[218:219], v[14:15]
	v_pk_mul_f32 v[14:15], v[88:89], v[8:9] op_sel_hi:[1,0]
	v_cvt_pk_bf16_f32 v10, v10, v11
	v_pk_mul_f32 v[12:13], v[220:221], v[14:15]
	v_pk_mul_f32 v[14:15], v[62:63], v[8:9] op_sel_hi:[1,0]
	v_cvt_pk_bf16_f32 v11, v12, v13
	global_store_dwordx2 v[48:49], v[10:11], off offset:32
	s_waitcnt vmcnt(15)
	v_pk_mul_f32 v[10:11], v[222:223], v[14:15]
	v_pk_mul_f32 v[14:15], v[58:59], v[8:9] op_sel_hi:[1,0]
	v_cvt_pk_bf16_f32 v10, v10, v11
	v_pk_mul_f32 v[12:13], v[224:225], v[14:15]
	v_pk_mul_f32 v[14:15], v[60:61], v[8:9] op_sel_hi:[1,0]
	v_cvt_pk_bf16_f32 v11, v12, v13
	global_store_dwordx2 v[48:49], v[10:11], off offset:48
	s_waitcnt vmcnt(15)
	v_pk_mul_f32 v[10:11], v[226:227], v[14:15]
	v_pk_mul_f32 v[14:15], v[54:55], v[8:9] op_sel_hi:[1,0]
	v_cvt_pk_bf16_f32 v10, v10, v11
	v_pk_mul_f32 v[12:13], v[228:229], v[14:15]
	v_pk_mul_f32 v[14:15], v[56:57], v[8:9] op_sel_hi:[1,0]
	v_cvt_pk_bf16_f32 v11, v12, v13
	global_store_dwordx2 v[48:49], v[10:11], off offset:64
	s_waitcnt vmcnt(15)
	v_pk_mul_f32 v[10:11], v[230:231], v[14:15]
	v_pk_mul_f32 v[14:15], v[50:51], v[8:9] op_sel_hi:[1,0]
	v_cvt_pk_bf16_f32 v10, v10, v11
	v_pk_mul_f32 v[12:13], v[232:233], v[14:15]
	v_pk_mul_f32 v[14:15], v[52:53], v[8:9] op_sel_hi:[1,0]
	v_cvt_pk_bf16_f32 v11, v12, v13
	global_store_dwordx2 v[48:49], v[10:11], off offset:80
	s_waitcnt vmcnt(15)
	v_pk_mul_f32 v[10:11], v[14:15], v[234:235]
	v_pk_mul_f32 v[14:15], v[42:43], v[8:9] op_sel_hi:[1,0]
	v_cvt_pk_bf16_f32 v10, v10, v11
	v_pk_mul_f32 v[12:13], v[14:15], v[236:237]
	v_pk_mul_f32 v[14:15], v[44:45], v[8:9] op_sel_hi:[1,0]
	v_cvt_pk_bf16_f32 v11, v12, v13
	global_store_dwordx2 v[48:49], v[10:11], off offset:96
	s_waitcnt vmcnt(15)
	v_pk_mul_f32 v[10:11], v[14:15], v[238:239]
	v_pk_mul_f32 v[14:15], v[38:39], v[8:9] op_sel_hi:[1,0]
	v_cvt_pk_bf16_f32 v10, v10, v11
	v_pk_mul_f32 v[12:13], v[14:15], v[240:241]
	v_pk_mul_f32 v[14:15], v[40:41], v[8:9] op_sel_hi:[1,0]
	v_cvt_pk_bf16_f32 v11, v12, v13
	global_store_dwordx2 v[48:49], v[10:11], off offset:112
	s_waitcnt vmcnt(15)
	v_pk_mul_f32 v[10:11], v[14:15], v[242:243]
	v_pk_mul_f32 v[14:15], v[34:35], v[8:9] op_sel_hi:[1,0]
	v_cvt_pk_bf16_f32 v10, v10, v11
	v_pk_mul_f32 v[12:13], v[14:15], v[244:245]
	v_pk_mul_f32 v[14:15], v[36:37], v[8:9] op_sel_hi:[1,0]
	v_cvt_pk_bf16_f32 v11, v12, v13
	global_store_dwordx2 v[48:49], v[10:11], off offset:128
	s_waitcnt vmcnt(15)
	v_pk_mul_f32 v[10:11], v[14:15], v[246:247]
	v_pk_mul_f32 v[14:15], v[32:33], v[8:9] op_sel_hi:[1,0]
	v_cvt_pk_bf16_f32 v10, v10, v11
	v_pk_mul_f32 v[12:13], v[14:15], v[248:249]
	v_pk_mul_f32 v[14:15], v[26:27], v[8:9] op_sel_hi:[1,0]
	v_cvt_pk_bf16_f32 v11, v12, v13
	global_store_dwordx2 v[48:49], v[10:11], off offset:144
	s_waitcnt vmcnt(15)
	v_pk_mul_f32 v[10:11], v[14:15], v[142:143]
	v_pk_mul_f32 v[14:15], v[22:23], v[8:9] op_sel_hi:[1,0]
	v_cvt_pk_bf16_f32 v10, v10, v11
	v_pk_mul_f32 v[12:13], v[14:15], v[144:145]
	v_pk_mul_f32 v[14:15], v[24:25], v[8:9] op_sel_hi:[1,0]
	v_cvt_pk_bf16_f32 v11, v12, v13
	global_store_dwordx2 v[48:49], v[10:11], off offset:160
	s_waitcnt vmcnt(15)
	v_pk_mul_f32 v[10:11], v[14:15], v[154:155]
	v_pk_mul_f32 v[14:15], v[18:19], v[8:9] op_sel_hi:[1,0]
	v_cvt_pk_bf16_f32 v10, v10, v11
	v_pk_mul_f32 v[12:13], v[14:15], v[156:157]
	v_pk_mul_f32 v[14:15], v[20:21], v[8:9] op_sel_hi:[1,0]
	v_cvt_pk_bf16_f32 v11, v12, v13
	global_store_dwordx2 v[48:49], v[10:11], off offset:176
	s_waitcnt vmcnt(15)
	v_pk_mul_f32 v[10:11], v[14:15], v[158:159]
	v_pk_mul_f32 v[14:15], v[16:17], v[8:9] op_sel_hi:[1,0]
	v_cvt_pk_bf16_f32 v10, v10, v11
	v_pk_mul_f32 v[12:13], v[14:15], v[160:161]
	s_nop 0
	v_cvt_pk_bf16_f32 v11, v12, v13
	global_store_dwordx2 v[48:49], v[10:11], off offset:192
	s_waitcnt vmcnt(15)
	v_pk_mul_f32 v[6:7], v[6:7], v[170:171]
	v_pk_mul_f32 v[2:3], v[2:3], v[172:173]
	v_cvt_pk_bf16_f32 v6, v6, v7
	v_cvt_pk_bf16_f32 v7, v2, v3
	global_store_dwordx2 v[48:49], v[6:7], off offset:208
	v_pk_mul_f32 v[2:3], v[4:5], v[8:9] op_sel_hi:[1,0]
	v_pk_mul_f32 v[4:5], v[64:65], v[8:9] op_sel_hi:[1,0]
	s_waitcnt vmcnt(15)
	v_pk_mul_f32 v[2:3], v[2:3], v[174:175]
	v_pk_mul_f32 v[0:1], v[0:1], v[176:177]
	v_cvt_pk_bf16_f32 v2, v2, v3
	v_cvt_pk_bf16_f32 v3, v0, v1
	global_store_dwordx2 v[48:49], v[2:3], off offset:224
	s_waitcnt vmcnt(15)
	v_pk_mul_f32 v[0:1], v[4:5], v[178:179]
	v_pk_mul_f32 v[4:5], v[66:67], v[8:9] op_sel_hi:[1,0]
	v_cvt_pk_bf16_f32 v0, v0, v1
	v_pk_mul_f32 v[2:3], v[4:5], v[180:181]
	s_nop 0
	v_cvt_pk_bf16_f32 v1, v2, v3
	global_store_dwordx2 v[48:49], v[0:1], off offset:240
	v_mov_b32_e32 v10, v174
	v_mov_b32_e32 v11, v175
	v_mov_b32_e32 v12, v176
	v_mov_b32_e32 v13, v177
	s_branch .LBB0_851
